# v38 plus retention output phase: per-item gain and gate loads issued before the MFMA section
# speedup vs baseline: 1.0064x; 1.0034x over previous
; #define ALDS __attribute__((address_space(3)))
; __device__ __forceinline__ unsigned cvtpk(float lo, float hi) { f32x2_t v = {lo, hi}; bf16x2_t b = __builtin_convertvector(v, bf16x2_t); return __builtin_bit_cast(unsigned, b); }
; __device__ __forceinline__ void wait_all_barrier() { asm volatile("s_waitcnt vmcnt(0) lgkmcnt(0)\n\ts_barrier" ::: "memory"); }
; __device__ __forceinline__ void r3_phase(ldsp lds, const bf16* U, const bf16* PREV, bf16* O, const float* gnw, int G, int bx, int wave, int lane) {
;     ...
;         ALDS float* red = (ALDS float*)(lds + RED_OFF + (k & 1) * 1024);
;         if (hh == 0) red[(et * 2 + it) * 32 + r] = ssq;
;         wait_all_barrier();
;         const float tot = (red[(0 * 2 + it) * 32 + r] + red[(1 * 2 + it) * 32 + r]) + (red[(2 * 2 + it) * 32 + r] + red[(3 * 2 + it) * 32 + r]);
;         const float rs = 1.0f / sqrtf(tot * (1.0f / 128.0f) + EPS);
;         const size_t tok = (size_t)b * SEQ + 64 * n + irow;
;         const float* gb = gnw; asm volatile("" : "+s"(gb));
;         const float* gp = gb + h * 128 + 32 * et + 4 * hh;
;         const bf16* gatep = U + tok * INW + 1536 + h * 128 + 32 * et + 4 * hh;
;         bf16* op = O + tok * D + h * 128 + 32 * et + 4 * hh;
;         f32x4 wq4[4]; v2u gq4[4];
; #pragma unroll
;         for (int g4 = 0; g4 < 4; ++g4) { wq4[g4] = *(const f32x4*)(gp + 8 * g4); gq4[g4] = *(const v2u*)(gatep + 8 * g4); }
; #pragma unroll
;         for (int g4 = 0; g4 < 4; ++g4) { const f32x4 w = wq4[g4]; const v2u gt = gq4[g4];
;             v2u pk; pk.x = cvtpk(oin[4 * g4] * rs * w[0] * bflo(gt.x), oin[4 * g4 + 1] * rs * w[1] * bfhi(gt.x));
;             pk.y = cvtpk(oin[4 * g4 + 2] * rs * w[2] * bflo(gt.y), oin[4 * g4 + 3] * rs * w[3] * bfhi(gt.y));
;             *(v2u*)(op + 8 * g4) = pk; }
.LBB0_360:
	s_or_b64 exec, exec, s[14:15]
	s_waitcnt vmcnt(0) lgkmcnt(0)
	s_barrier
	v_lshl_add_u32 v8, v60, 2, s37
	s_add_i32 s15, s37, s31
	ds_read_b32 v28, v8
	v_lshl_add_u32 v8, v59, 2, s15
	s_ashr_i32 s14, s26, 6
	ds_read2st64_b32 v[30:31], v8 offset0:1 offset1:2
	v_lshl_add_u32 v8, v71, 2, s37
	s_lshl_b32 s37, s26, 6
	s_mulk_i32 s26, 0xfd00
	s_ashr_i32 s15, s14, 31
	s_add_i32 s52, s41, s26
	s_lshl_b64 s[14:15], s[14:15], 12
	s_and_b32 s37, s37, 0xfc0
	s_ashr_i32 s53, s52, 31
	s_or_b32 s14, s14, s37
	s_mov_b64 s[50:51], s[18:19]
	s_lshl_b64 s[54:55], s[52:53], 2
	ds_read_b32 v46, v8
	v_or_b32_e32 v24, s14, v60
	s_add_u32 s14, s50, s54
	s_addc_u32 s26, s51, s55
	s_lshl_b32 s37, s33, 2
	s_add_u32 s50, s14, s37
	s_addc_u32 s51, s26, 0
	v_lshlrev_b32_e32 v50, 2, v62
	s_waitcnt lgkmcnt(3)
	v_mov_b64_e32 v[8:9], s[22:23]
	v_lshl_add_u64 v[26:27], s[50:51], 0, v[50:51]
	v_mad_u64_u32 v[8:9], s[50:51], v24, s40, v[8:9]
	v_mad_i32_i24 v9, s15, v127, v9
	s_lshl_b64 s[50:51], s[52:53], 1
	v_lshl_add_u64 v[8:9], v[8:9], 0, s[50:51]
	s_lshl_b32 s26, s33, 1
	v_lshl_add_u64 v[8:9], v[8:9], 0, s[26:27]
	v_lshlrev_b32_e32 v50, 1, v62
	v_lshl_add_u64 v[36:37], v[8:9], 0, v[50:51]
	s_nop 0
	s_nop 0
	s_nop 0
	s_nop 0
	s_nop 0
	s_nop 0
	v_mov_b32_e32 v25, s15
	v_lshlrev_b64 v[44:45], 11, v[24:25]
	s_nop 0
	s_nop 0
	s_nop 0
	s_waitcnt lgkmcnt(0)
	v_mov_b32_e32 v29, v31
	v_mov_b32_e32 v31, v46
	v_pk_add_f32 v[28:29], v[28:29], v[30:31]
	s_add_i32 s48, s48, 1
	v_add_f32_e32 v28, v28, v29
	v_fmamk_f32 v28, v28, 0x3c000000, v125
	v_mul_f32_e32 v29, 0x4f800000, v28
	v_cmp_gt_f32_e32 vcc, s47, v28
	s_add_i32 s41, s41, s42
	s_add_i32 s43, s43, s44
	v_cndmask_b32_e32 v30, v28, v29, vcc
	v_sqrt_f32_e32 v31, v30
	v_lshl_add_u64 v[28:29], s[24:25], 0, v[44:45]
	v_lshl_add_u64 v[28:29], v[28:29], 0, s[50:51]
	v_lshl_add_u64 v[28:29], v[28:29], 0, s[26:27]
	v_add_u32_e32 v44, -1, v31
	v_add_u32_e32 v45, 1, v31
	v_fma_f32 v46, -v44, v31, v30
	v_fma_f32 v47, -v45, v31, v30
	v_cmp_ge_f32_e64 s[14:15], 0, v46
	v_lshl_add_u64 v[28:29], v[28:29], 0, v[50:51]
	s_nop 0
	v_cndmask_b32_e64 v31, v31, v44, s[14:15]
	v_cmp_lt_f32_e64 s[14:15], 0, v47
	s_nop 1
	v_cndmask_b32_e64 v31, v31, v45, s[14:15]
	v_mul_f32_e32 v44, 0x37800000, v31
	v_cndmask_b32_e32 v31, v31, v44, vcc
	v_cmp_class_f32_e32 vcc, v30, v126
	s_nop 1
	v_cndmask_b32_e32 v30, v31, v30, vcc
	v_div_scale_f32 v31, s[14:15], v30, v30, 1.0
	v_rcp_f32_e32 v44, v31
	v_div_scale_f32 v45, vcc, 1.0, v30, 1.0
	s_mov_b32 s15, s36
	v_fma_f32 v46, -v31, v44, 1.0
	v_fmac_f32_e32 v44, v46, v44
	v_mul_f32_e32 v46, v45, v44
	v_fma_f32 v47, -v31, v46, v45
	v_fmac_f32_e32 v46, v47, v44
	v_fma_f32 v31, -v31, v46, v45
	v_div_fmas_f32 v31, v31, v44, v46
	v_div_fixup_f32 v30, v31, v30, 1.0
	v_pk_mul_f32 v[34:35], v[34:35], v[30:31] op_sel_hi:[1,0]
	v_pk_mul_f32 v[32:33], v[32:33], v[30:31] op_sel_hi:[1,0]
	v_pk_mul_f32 v[6:7], v[6:7], v[30:31] op_sel_hi:[1,0]
	v_pk_mul_f32 v[4:5], v[4:5], v[30:31] op_sel_hi:[1,0]
	v_pk_mul_f32 v[2:3], v[2:3], v[30:31] op_sel_hi:[1,0]
	v_pk_mul_f32 v[0:1], v[0:1], v[30:31] op_sel_hi:[1,0]
	s_andn2_b64 vcc, exec, s[38:39]
	s_waitcnt vmcnt(0)
	v_pk_mul_f32 v[8:9], v[160:161], v[34:35]
	v_lshlrev_b32_e32 v34, 16, v176
	v_and_b32_e32 v35, 0xffff0000, v176
	v_pk_mul_f32 v[10:11], v[162:163], v[32:33]
	v_lshlrev_b32_e32 v32, 16, v177
	v_and_b32_e32 v33, 0xffff0000, v177
	v_pk_mul_f32 v[8:9], v[8:9], v[34:35]
	v_pk_mul_f32 v[10:11], v[10:11], v[32:33]
	v_cvt_pk_bf16_f32 v8, v8, v9
	v_cvt_pk_bf16_f32 v9, v10, v11
	global_store_dwordx2 v[28:29], v[8:9], off
	v_pk_mul_f32 v[8:9], v[18:19], v[30:31] op_sel_hi:[1,0]
	v_lshlrev_b32_e32 v10, 16, v178
	v_pk_mul_f32 v[8:9], v[164:165], v[8:9]
	v_and_b32_e32 v11, 0xffff0000, v178
	v_pk_mul_f32 v[8:9], v[8:9], v[10:11]
	v_pk_mul_f32 v[10:11], v[16:17], v[30:31] op_sel_hi:[1,0]
	v_lshlrev_b32_e32 v12, 16, v179
	v_pk_mul_f32 v[10:11], v[166:167], v[10:11]
	v_and_b32_e32 v13, 0xffff0000, v179
	v_pk_mul_f32 v[10:11], v[10:11], v[12:13]
	v_cvt_pk_bf16_f32 v8, v8, v9
	v_cvt_pk_bf16_f32 v9, v10, v11
	global_store_dwordx2 v[28:29], v[8:9], off offset:16
	v_pk_mul_f32 v[6:7], v[6:7], v[168:169]
	v_lshlrev_b32_e32 v8, 16, v180
	v_and_b32_e32 v9, 0xffff0000, v180
	v_pk_mul_f32 v[6:7], v[6:7], v[8:9]
	v_pk_mul_f32 v[4:5], v[4:5], v[170:171]
	v_lshlrev_b32_e32 v8, 16, v181
	v_and_b32_e32 v9, 0xffff0000, v181
	v_pk_mul_f32 v[4:5], v[4:5], v[8:9]
	v_cvt_pk_bf16_f32 v6, v6, v7
	v_cvt_pk_bf16_f32 v7, v4, v5
	v_pk_mul_f32 v[2:3], v[2:3], v[172:173]
	v_lshlrev_b32_e32 v4, 16, v182
	v_and_b32_e32 v5, 0xffff0000, v182
	v_pk_mul_f32 v[2:3], v[2:3], v[4:5]
	v_pk_mul_f32 v[0:1], v[0:1], v[174:175]
	v_lshlrev_b32_e32 v4, 16, v183
	v_and_b32_e32 v5, 0xffff0000, v183
	v_pk_mul_f32 v[0:1], v[0:1], v[4:5]
	v_cvt_pk_bf16_f32 v2, v2, v3
	v_cvt_pk_bf16_f32 v3, v0, v1
	global_store_dwordx2 v[28:29], v[6:7], off offset:32
	global_store_dwordx2 v[28:29], v[2:3], off offset:48
	s_cbranch_vccz .LBB0_365

; #define ALDS __attribute__((address_space(3)))
; __device__ __forceinline__ void r3_phase(ldsp lds, const bf16* U, const bf16* PREV, bf16* O, const float* gnw, int G, int bx, int wave, int lane) {
;     ...
;     for (int item = bx; item < N_ITEMS; item += G, ++k) {
;         const unsigned st = lds0 + (k & 1) * STAGE;
;         if (item + G < N_ITEMS) stage_item<true>(lds, ((k + 1) & 1) * STAGE, item + G, U, PREV, wave, lane);
;         int b, n, h; decode(item, b, n, h);
;         const float lg2 = log2f(1.0f - exp2f(-5.0f - (float)h));
;         bf16x8 qf[4];
; #pragma unroll
;         for (int ks = 0; ks < 4; ++ks) qf[ks] = *(const ALDS bf16x8*)(size_t)(st + off_b(32u * it + r, 8u + 2u * ks + hh));
;         bf16x8 pa[2][2];
;         const int irow = 32 * it + r;
; #pragma unroll
;         for (int sub = 0; sub < 2; ++sub) {
;             f32x16 s;
; #pragma unroll
;             for (int i = 0; i < 16; ++i) s[i] = 0.f;
; #pragma unroll
;             for (int ks = 0; ks < 4; ++ks) { const bf16x8 kf = *(const ALDS bf16x8*)(size_t)(st + off_b(32u * sub + r, 2u * ks + hh)); s = __builtin_amdgcn_mfma_f32_32x32x16_bf16(kf, qf[ks], s, 0, 0, 0); }
; #pragma unroll
;             for (int i = 0; i < 16; ++i) { const int jrow = 32 * sub + (i & 3) + 8 * (i >> 2) + 4 * hh; s[i] *= __builtin_amdgcn_exp2f(lg2 * fabsf((float)(irow - jrow))); }
;             pa[sub][0] = pack8s(s, 0); pa[sub][1] = pack8s(s, 8);
;         }
;     ...
;         const size_t tok = (size_t)b * SEQ + 64 * n + irow;
;         const float* gb = gnw; asm volatile("" : "+s"(gb));
;         const float* gp = gb + h * 128 + 32 * et + 4 * hh;
;         const bf16* gatep = U + tok * INW + 1536 + h * 128 + 32 * et + 4 * hh;
;         bf16* op = O + tok * D + h * 128 + 32 * et + 4 * hh;
;         f32x4 wq4[4]; v2u gq4[4];
; #pragma unroll
;         for (int g4 = 0; g4 < 4; ++g4) { wq4[g4] = *(const f32x4*)(gp + 8 * g4); gq4[g4] = *(const v2u*)(gatep + 8 * g4); }
.LBB0_363:
	s_mul_hi_i32 s26, s15, 0x2aaaaaab
	s_lshr_b32 s37, s26, 31
	s_add_i32 s26, s26, s37
	s_ashr_i32 s62, s26, 6
	s_lshl_b32 s64, s26, 6
	s_mul_i32 s65, s26, 0xfffffd00
	s_ashr_i32 s63, s62, 31
	s_add_i32 s66, s41, s65
	s_lshl_b64 s[62:63], s[62:63], 12
	s_and_b32 s64, s64, 0xfc0
	s_ashr_i32 s67, s66, 31
	s_or_b32 s62, s62, s64
	s_lshl_b64 s[68:69], s[66:67], 2
	v_or_b32_e32 v184, s62, v60
	s_add_u32 s68, s18, s68
	s_addc_u32 s69, s19, s69
	s_lshl_b32 s64, s33, 2
	s_add_u32 s68, s68, s64
	s_addc_u32 s69, s69, 0
	v_lshlrev_b32_e32 v186, 2, v62
	v_mov_b32_e32 v187, v51
	v_mov_b64_e32 v[188:189], s[22:23]
	v_lshl_add_u64 v[190:191], s[68:69], 0, v[186:187]
	v_mad_u64_u32 v[188:189], vcc, v184, s40, v[188:189]
	v_mad_i32_i24 v189, s63, v127, v189
	s_lshl_b64 s[68:69], s[66:67], 1
	v_lshl_add_u64 v[188:189], v[188:189], 0, s[68:69]
	s_lshl_b32 s74, s33, 1
	s_mov_b32 s75, s27
	v_lshl_add_u64 v[188:189], v[188:189], 0, s[74:75]
	v_lshlrev_b32_e32 v186, 1, v62
	v_lshl_add_u64 v[192:193], v[188:189], 0, v[186:187]
	global_load_dwordx4 v[160:163], v[190:191], off
	global_load_dwordx2 v[176:177], v[192:193], off offset:3072
	global_load_dwordx4 v[164:167], v[190:191], off offset:32
	global_load_dwordx2 v[178:179], v[192:193], off offset:3088
	global_load_dwordx4 v[168:171], v[190:191], off offset:64
	global_load_dwordx2 v[180:181], v[192:193], off offset:3104
	global_load_dwordx4 v[172:175], v[190:191], off offset:96
	global_load_dwordx2 v[182:183], v[192:193], off offset:3120
	s_mul_i32 s37, s26, -6
	s_add_i32 s15, s15, s37
	v_cvt_f32_i32_e32 v0, s15
	s_mul_i32 s15, s14, 0xc000
	s_add_i32 s37, s15, 0
	v_add_u32_e32 v24, s37, v61
	v_sub_f32_e32 v0, 0xc0a00000, v0
	v_cmp_gt_f32_e32 vcc, s45, v0
	v_add_u32_e32 v25, s37, v63
	v_add_u32_e32 v5, v25, v72
	v_cndmask_b32_e32 v1, 0, v130, vcc
	v_add_f32_e32 v0, v0, v1
	v_exp_f32_e32 v4, v0
	v_add_u32_e32 v0, v24, v76
	ds_read_b128 v[0:3], v0
	ds_read_b128 v[44:47], v5
	s_and_b64 s[50:51], vcc, exec
	s_cselect_b32 s37, 0xffffffc0, 0
	v_ldexp_f32 v26, v4, s37
	v_add_u32_e32 v4, v24, v77
	ds_read_b128 v[4:7], v4
	s_waitcnt lgkmcnt(1)
	v_mfma_f32_32x32x16_bf16 v[8:23], v[0:3], v[44:47], 0
	v_add_u32_e32 v0, v25, v73
	ds_read_b128 v[40:43], v0
	v_add_u32_e32 v0, v25, v74
	ds_read_b128 v[36:39], v0
	v_add_u32_e32 v0, v24, v78
	ds_read_b128 v[0:3], v0
	v_sub_f32_e32 v26, 1.0, v26
	s_waitcnt lgkmcnt(2)
	v_mfma_f32_32x32x16_bf16 v[8:23], v[4:7], v[40:43], v[8:23]
	v_add_u32_e32 v4, v25, v75
	ds_read_b128 v[32:35], v4
	v_add_u32_e32 v4, v24, v79
	ds_read_b128 v[4:7], v4
	v_cmp_gt_f32_e32 vcc, s46, v26
	s_and_b64 s[50:51], vcc, exec
	s_cselect_b32 s37, 32, 0
	s_waitcnt lgkmcnt(2)
	v_mfma_f32_32x32x16_bf16 v[8:23], v[0:3], v[36:39], v[8:23]
	v_ldexp_f32 v0, v26, s37
	v_log_f32_e32 v0, v0
	v_cndmask_b32_e32 v25, 0, v131, vcc
	v_add_u32_e32 v144, 0x2000, v24
	s_lshl_b32 s14, s14, 10
	v_sub_f32_e32 v50, v0, v25
	v_mul_f32_e64 v0, |v80|, v50
	s_waitcnt lgkmcnt(0)
	v_mfma_f32_32x32x16_bf16 v[8:23], v[4:7], v[32:35], v[8:23]
	v_mul_f32_e64 v1, |v81|, v50
	v_exp_f32_e32 v0, v0
	v_exp_f32_e32 v1, v1
	v_mul_f32_e64 v2, |v82|, v50
	v_mul_f32_e64 v3, |v83|, v50
	v_exp_f32_e32 v2, v2
	v_exp_f32_e32 v3, v3
	s_nop 4
	v_pk_mul_f32 v[28:29], v[0:1], v[8:9]
	v_mul_f32_e64 v0, |v88|, v50
	v_exp_f32_e32 v136, v0
	v_mul_f32_e64 v0, |v89|, v50
	v_exp_f32_e32 v137, v0
	v_mul_f32_e64 v0, |v90|, v50
	v_exp_f32_e32 v138, v0
	v_mul_f32_e64 v0, |v91|, v50
	v_mul_f32_e64 v4, |v84|, v50
	v_mul_f32_e64 v5, |v85|, v50
	v_exp_f32_e32 v139, v0
	v_add_u32_e32 v0, v144, v76
	v_exp_f32_e32 v4, v4
	v_exp_f32_e32 v5, v5
	v_pk_mul_f32 v[30:31], v[2:3], v[10:11]
	ds_read_b128 v[0:3], v0
	v_mul_f32_e64 v6, |v86|, v50
	v_mul_f32_e64 v7, |v87|, v50
	v_pk_mul_f32 v[132:133], v[4:5], v[12:13]
	v_mul_f32_e64 v4, |v92|, v50
	v_exp_f32_e32 v6, v6
	v_exp_f32_e32 v7, v7
	v_exp_f32_e32 v140, v4
	v_mul_f32_e64 v4, |v93|, v50
	v_exp_f32_e32 v141, v4
	v_mul_f32_e64 v4, |v94|, v50
	v_exp_f32_e32 v142, v4
	v_add_u32_e32 v4, v144, v77
	ds_read_b128 v[24:27], v4
	v_pk_mul_f32 v[134:135], v[6:7], v[14:15]
	s_waitcnt lgkmcnt(1)
	v_mfma_f32_32x32x16_bf16 v[0:15], v[0:3], v[44:47], 0
	v_mul_f32_e64 v136, v136, v16
	v_mul_f32_e64 v137, v137, v17
	v_add_u32_e32 v16, v144, v78
	v_mul_f32_e64 v138, v138, v18
	v_mul_f32_e64 v139, v139, v19
	ds_read_b128 v[16:19], v16
	v_mul_f32_e64 v143, |v95|, v50
	v_exp_f32_e32 v143, v143
	v_pk_mul_f32 v[140:141], v[140:141], v[20:21]
	s_waitcnt lgkmcnt(1)
	v_mfma_f32_32x32x16_bf16 v[0:15], v[24:27], v[40:43], v[0:15]
	v_add_u32_e32 v24, v144, v79
	ds_read_b128 v[24:27], v24
	v_mul_f32_e64 v142, v142, v22
	v_mul_f32_e64 v143, v143, v23
	v_cvt_pk_bf16_f32 v23, v134, v135
	v_cvt_pk_bf16_f32 v134, v140, v141
	v_cvt_pk_bf16_f32 v135, v142, v143
	v_cvt_pk_bf16_f32 v20, v28, v29
	s_waitcnt lgkmcnt(1)
	v_mfma_f32_32x32x16_bf16 v[0:15], v[16:19], v[36:39], v[0:15]
	v_mul_f32_e64 v16, |v96|, v50
	v_mul_f32_e64 v17, |v97|, v50
	v_exp_f32_e32 v16, v16
	v_exp_f32_e32 v17, v17
	v_mul_f32_e64 v18, |v102|, v50
	v_mul_f32_e64 v19, |v103|, v50
	v_exp_f32_e32 v18, v18
	s_waitcnt lgkmcnt(0)
; #define ALDS __attribute__((address_space(3)))
; __device__ __forceinline__ void r3_phase(ldsp lds, const bf16* U, const bf16* PREV, bf16* O, const float* gnw, int G, int bx, int wave, int lane) {
;     ...
;         f32x16 oin, ox;
; #pragma unroll
;         for (int i = 0; i < 16; ++i) { oin[i] = 0.f; ox[i] = 0.f; }
; #pragma unroll
;         for (int sub = 0; sub < 2; ++sub)
; #pragma unroll
;             for (int s2 = 0; s2 < 2; ++s2) oin = __builtin_amdgcn_mfma_f32_32x32x16_bf16(tr_perm(st + 16384, et, sub, s2, lane), pa[sub][s2], oin, 0, 0, 0);
; #pragma unroll
;         for (int ks = 0; ks < 4; ++ks) ox = __builtin_amdgcn_mfma_f32_32x32x16_bf16(tr_nat(st + 32768, et, ks, lane), qf[ks], ox, 0, 0, 0);
;         const float dec = __builtin_amdgcn_exp2f(lg2 * (float)(irow + 1));
;         float ssq = 0.f;
; #pragma unroll
;         for (int i = 0; i < 16; ++i) { oin[i] = fmaf(dec, ox[i], oin[i]); ssq += oin[i] * oin[i]; }
;         ssq += shx(ssq, 32);
;         ALDS float* red = (ALDS float*)(lds + RED_OFF + (k & 1) * 1024);
;         if (hh == 0) red[(et * 2 + it) * 32 + r] = ssq;
	v_mfma_f32_32x32x16_bf16 v[0:15], v[24:27], v[32:35], v[0:15]
	v_mul_f32_e64 v24, |v104|, v50
	v_mul_f32_e64 v25, |v105|, v50
	v_exp_f32_e32 v24, v24
	v_exp_f32_e32 v25, v25
	v_exp_f32_e32 v19, v19
	v_cvt_pk_bf16_f32 v21, v30, v31
	v_cvt_pk_bf16_f32 v22, v132, v133
	s_nop 4
	v_pk_mul_f32 v[140:141], v[16:17], v[0:1]
	v_mul_f32_e64 v0, |v98|, v50
	v_mul_f32_e64 v1, |v99|, v50
	v_exp_f32_e32 v0, v0
	v_exp_f32_e32 v1, v1
	v_pk_mul_f32 v[148:149], v[24:25], v[8:9]
	v_mul_f32_e64 v16, |v100|, v50
	v_mul_f32_e64 v17, |v101|, v50
	v_pk_mul_f32 v[142:143], v[0:1], v[2:3]
	v_add_u32_e32 v2, s15, v67
	v_mul_f32_e64 v0, |v106|, v50
	v_add_u32_e32 v156, v2, v66
	v_exp_f32_e32 v150, v0
	v_add_u32_e32 v0, v156, v112
	v_add_u32_e32 v8, v113, v2
	ds_read_b64_tr_b16 v[0:1], v0
	ds_read_b64_tr_b16 v[2:3], v8 offset:2048
	v_exp_f32_e32 v16, v16
	v_exp_f32_e32 v17, v17
	v_pk_mul_f32 v[146:147], v[18:19], v[6:7]
	v_cvt_pk_bf16_f32 v133, v138, v139
	v_cvt_pk_bf16_f32 v132, v136, v137
	v_pk_mul_f32 v[144:145], v[16:17], v[4:5]
	s_waitcnt lgkmcnt(0)
	v_mfma_f32_32x32x16_bf16 v[16:31], v[0:3], v[20:23], 0
	v_mul_f32_e64 v4, |v107|, v50
	v_exp_f32_e32 v151, v4
	v_mul_f32_e64 v4, |v108|, v50
	v_exp_f32_e32 v152, v4
	v_add_u32_e32 v4, v114, v156
	ds_read_b64_tr_b16 v[4:5], v4
	ds_read_b64_tr_b16 v[6:7], v8 offset:6144
	ds_read_b64_tr_b16 v[138:139], v8 offset:10240
	ds_read_b64_tr_b16 v[8:9], v8 offset:14336
	v_add_u32_e32 v1, v115, v156
	ds_read_b64_tr_b16 v[136:137], v1
	s_waitcnt lgkmcnt(3)
	v_mfma_f32_32x32x16_bf16 v[16:31], v[4:7], v[132:135], v[16:31]
	v_mul_f32_e64 v0, |v109|, v50
	v_exp_f32_e32 v153, v0
	v_mul_f32_e64 v0, |v110|, v50
	v_exp_f32_e32 v154, v0
	v_mul_f32_e64 v0, |v111|, v50
	v_add_u32_e32 v4, v116, v156
	v_exp_f32_e32 v155, v0
	v_cvt_pk_bf16_f32 v0, v140, v141
	v_cvt_pk_bf16_f32 v1, v142, v143
	v_cvt_pk_bf16_f32 v2, v144, v145
	v_cvt_pk_bf16_f32 v3, v146, v147
	ds_read_b64_tr_b16 v[6:7], v4
	v_pk_mul_f32 v[4:5], v[152:153], v[12:13]
	s_waitcnt lgkmcnt(1)
	v_mfma_f32_32x32x16_bf16 v[16:31], v[136:139], v[0:3], v[16:31]
	v_mul_f32_e64 v2, v150, v10
	v_mul_f32_e64 v3, v151, v11
	v_mul_f32_e64 v10, v154, v14
	v_mul_f32_e64 v11, v155, v15
	v_add_u32_e32 v132, s15, v69
	v_cvt_pk_bf16_f32 v0, v148, v149
	v_cvt_pk_bf16_f32 v1, v2, v3
	v_cvt_pk_bf16_f32 v2, v4, v5
	v_cvt_pk_bf16_f32 v3, v10, v11
	v_add_u32_e32 v133, v132, v68
	s_add_i32 s37, s14, 0
	s_waitcnt lgkmcnt(0)
	v_mfma_f32_32x32x16_bf16 v[16:31], v[6:9], v[0:3], v[16:31]
	v_add_u32_e32 v0, v133, v117
	v_add_u32_e32 v2, v132, v118
	ds_read_b64_tr_b16 v[0:1], v0
	ds_read_b64_tr_b16 v[2:3], v2
	s_add_i32 s37, s37, 0x18000
	s_waitcnt lgkmcnt(0)
	v_mfma_f32_32x32x16_bf16 v[0:15], v[0:3], v[44:47], 0
	v_add_u32_e32 v44, v119, v133
	v_add_u32_e32 v46, v132, v120
	ds_read_b64_tr_b16 v[44:45], v44
	ds_read_b64_tr_b16 v[46:47], v46
	s_waitcnt lgkmcnt(0)
	v_mfma_f32_32x32x16_bf16 v[0:15], v[44:47], v[40:43], v[0:15]
	v_add_u32_e32 v40, v121, v133
	v_add_u32_e32 v42, v132, v122
	ds_read_b64_tr_b16 v[40:41], v40
	ds_read_b64_tr_b16 v[42:43], v42
	s_waitcnt lgkmcnt(0)
	v_mfma_f32_32x32x16_bf16 v[0:15], v[40:43], v[36:39], v[0:15]
	v_add_u32_e32 v36, v123, v133
	v_add_u32_e32 v38, v132, v124
	ds_read_b64_tr_b16 v[36:37], v36
	ds_read_b64_tr_b16 v[38:39], v38
	v_mul_f32_e32 v40, v50, v70
	v_exp_f32_e32 v40, v40
	s_waitcnt lgkmcnt(0)
	v_mfma_f32_32x32x16_bf16 v[0:15], v[36:39], v[32:35], v[0:15]
	s_nop 11
	v_pk_fma_f32 v[34:35], v[40:41], v[0:1], v[16:17] op_sel_hi:[0,1,1]
	v_pk_mul_f32 v[36:37], v[34:35], v[34:35]
	v_pk_fma_f32 v[32:33], v[40:41], v[2:3], v[18:19] op_sel_hi:[0,1,1]
	v_pk_mul_f32 v[38:39], v[32:33], v[32:33]
	v_pk_fma_f32 v[16:17], v[40:41], v[6:7], v[22:23] op_sel_hi:[0,1,1]
	v_pk_fma_f32 v[6:7], v[40:41], v[8:9], v[24:25] op_sel_hi:[0,1,1]
	v_add_f32_e32 v24, v36, v37
	v_pk_fma_f32 v[18:19], v[40:41], v[4:5], v[20:21] op_sel_hi:[0,1,1]
	v_add_f32_e32 v24, v38, v24
	v_pk_mul_f32 v[20:21], v[18:19], v[18:19]
	v_add_f32_e32 v24, v39, v24
	v_add_f32_e32 v20, v20, v24
	v_pk_mul_f32 v[22:23], v[16:17], v[16:17]
	v_add_f32_e32 v20, v21, v20
	v_add_f32_e32 v20, v22, v20
	v_pk_mul_f32 v[8:9], v[6:7], v[6:7]
	v_add_f32_e32 v20, v23, v20
	v_pk_fma_f32 v[4:5], v[40:41], v[10:11], v[26:27] op_sel_hi:[0,1,1]
	v_add_f32_e32 v8, v8, v20
	v_pk_mul_f32 v[10:11], v[4:5], v[4:5]
	v_add_f32_e32 v8, v9, v8
	v_pk_fma_f32 v[2:3], v[40:41], v[12:13], v[28:29] op_sel_hi:[0,1,1]
	v_add_f32_e32 v8, v10, v8
	v_pk_mul_f32 v[12:13], v[2:3], v[2:3]
	v_add_f32_e32 v8, v11, v8
	v_pk_fma_f32 v[0:1], v[40:41], v[14:15], v[30:31] op_sel_hi:[0,1,1]
	v_add_f32_e32 v8, v12, v8
	v_mov_b32_e32 v9, v201
	v_pk_mul_f32 v[14:15], v[0:1], v[0:1]
	v_add_f32_e32 v8, v13, v8
	v_add_f32_e32 v8, v14, v8
	v_lshlrev_b32_e32 v9, 2, v9
	v_add_f32_e32 v8, v15, v8
	v_xor_b32_e32 v9, 0x80, v9
	ds_bpermute_b32 v9, v9, v8
	s_and_saveexec_b64 s[14:15], s[12:13]
	s_cbranch_execz .LBB0_360
	s_add_i32 s49, s37, s30
	v_lshl_add_u32 v10, v49, 2, s49
	s_waitcnt lgkmcnt(0)
	v_add_f32_e32 v8, v8, v9
	ds_write_b32 v10, v8
	s_branch .LBB0_360

; #define ALDS __attribute__((address_space(3)))
; __device__ __forceinline__ unsigned cvtpk(float lo, float hi) { f32x2_t v = {lo, hi}; bf16x2_t b = __builtin_convertvector(v, bf16x2_t); return __builtin_bit_cast(unsigned, b); }
; __device__ __forceinline__ void wait_all_barrier() { asm volatile("s_waitcnt vmcnt(0) lgkmcnt(0)\n\ts_barrier" ::: "memory"); }
; __device__ __forceinline__ void r3_phase(ldsp lds, const bf16* U, const bf16* PREV, bf16* O, const float* gnw, int G, int bx, int wave, int lane) {
;     ...
;         ALDS float* red = (ALDS float*)(lds + RED_OFF + (k & 1) * 1024);
;         if (hh == 0) red[(et * 2 + it) * 32 + r] = ssq;
;         wait_all_barrier();
;         const float tot = (red[(0 * 2 + it) * 32 + r] + red[(1 * 2 + it) * 32 + r]) + (red[(2 * 2 + it) * 32 + r] + red[(3 * 2 + it) * 32 + r]);
;         const float rs = 1.0f / sqrtf(tot * (1.0f / 128.0f) + EPS);
;         const size_t tok = (size_t)b * SEQ + 64 * n + irow;
;         const float* gb = gnw; asm volatile("" : "+s"(gb));
;         const float* gp = gb + h * 128 + 32 * et + 4 * hh;
;         const bf16* gatep = U + tok * INW + 1536 + h * 128 + 32 * et + 4 * hh;
;         bf16* op = O + tok * D + h * 128 + 32 * et + 4 * hh;
;         f32x4 wq4[4]; v2u gq4[4];
; #pragma unroll
;         for (int g4 = 0; g4 < 4; ++g4) { wq4[g4] = *(const f32x4*)(gp + 8 * g4); gq4[g4] = *(const v2u*)(gatep + 8 * g4); }
; #pragma unroll
;         for (int g4 = 0; g4 < 4; ++g4) { const f32x4 w = wq4[g4]; const v2u gt = gq4[g4];
;             v2u pk; pk.x = cvtpk(oin[4 * g4] * rs * w[0] * bflo(gt.x), oin[4 * g4 + 1] * rs * w[1] * bfhi(gt.x));
;             pk.y = cvtpk(oin[4 * g4 + 2] * rs * w[2] * bflo(gt.y), oin[4 * g4 + 3] * rs * w[3] * bfhi(gt.y));
;             *(v2u*)(op + 8 * g4) = pk; }
.LBB0_1428:
	s_or_b64 exec, exec, s[18:19]
	s_waitcnt vmcnt(0) lgkmcnt(0)
	s_barrier
	v_lshl_add_u32 v8, v60, 2, s45
	s_add_i32 s4, s45, s6
	s_ashr_i32 s18, s26, 6
	ds_read_b32 v28, v8
	v_lshl_add_u32 v8, v59, 2, s4
	s_lshl_b32 s4, s26, 6
	s_mulk_i32 s26, 0xfd00
	s_ashr_i32 s19, s18, 31
	s_add_i32 s52, s33, s26
	s_lshl_b64 s[18:19], s[18:19], 12
	s_and_b32 s4, s4, 0xfc0
	s_ashr_i32 s53, s52, 31
	ds_read2st64_b32 v[30:31], v8 offset0:1 offset1:2
	v_lshl_add_u32 v8, v71, 2, s45
	s_or_b32 s4, s18, s4
	s_mov_b64 s[50:51], s[24:25]
	s_lshl_b64 s[54:55], s[52:53], 2
	ds_read_b32 v46, v8
	v_or_b32_e32 v24, s4, v60
	s_add_u32 s4, s50, s54
	s_addc_u32 s5, s51, s55
	s_lshl_b32 s18, s12, 2
	s_add_u32 s50, s4, s18
	s_addc_u32 s51, s5, 0
	v_lshlrev_b32_e32 v50, 2, v62
	s_waitcnt lgkmcnt(3)
	v_mov_b64_e32 v[8:9], s[20:21]
	v_lshl_add_u64 v[26:27], s[50:51], 0, v[50:51]
	v_mad_u64_u32 v[8:9], s[50:51], v24, s13, v[8:9]
	v_mad_i32_i24 v9, s19, v127, v9
	s_lshl_b64 s[50:51], s[52:53], 1
	v_lshl_add_u64 v[8:9], v[8:9], 0, s[50:51]
	s_lshl_b32 s26, s12, 1
	v_lshl_add_u64 v[8:9], v[8:9], 0, s[26:27]
	v_lshlrev_b32_e32 v50, 1, v62
	v_lshl_add_u64 v[36:37], v[8:9], 0, v[50:51]
	s_nop 0
	s_nop 0
	s_nop 0
	s_nop 0
	s_nop 0
	s_nop 0
	v_mov_b32_e32 v25, s19
	v_lshlrev_b64 v[44:45], 11, v[24:25]
	s_nop 0
	s_nop 0
	s_nop 0
	s_waitcnt lgkmcnt(0)
	v_mov_b32_e32 v29, v31
	v_mov_b32_e32 v31, v46
	v_pk_add_f32 v[28:29], v[28:29], v[30:31]
	s_mov_b32 s4, 0xf800000
	v_add_f32_e32 v28, v28, v29
	v_fmamk_f32 v28, v28, 0x3c000000, v125
	v_mul_f32_e32 v29, 0x4f800000, v28
	v_cmp_gt_f32_e32 vcc, s4, v28
	s_add_i32 s49, s49, 1
	s_add_i32 s33, s33, s40
	v_cndmask_b32_e32 v30, v28, v29, vcc
	v_sqrt_f32_e32 v31, v30
	v_lshl_add_u64 v[28:29], s[22:23], 0, v[44:45]
	v_lshl_add_u64 v[28:29], v[28:29], 0, s[50:51]
	v_lshl_add_u64 v[28:29], v[28:29], 0, s[26:27]
	v_add_u32_e32 v44, -1, v31
	v_add_u32_e32 v45, 1, v31
	v_fma_f32 v46, -v44, v31, v30
	v_fma_f32 v47, -v45, v31, v30
	v_cmp_ge_f32_e64 s[18:19], 0, v46
	v_lshl_add_u64 v[28:29], v[28:29], 0, v[50:51]
	s_add_i32 s41, s41, s48
	v_cndmask_b32_e64 v31, v31, v44, s[18:19]
	v_cmp_lt_f32_e64 s[18:19], 0, v47
	s_nop 1
	v_cndmask_b32_e64 v31, v31, v45, s[18:19]
	v_mul_f32_e32 v44, 0x37800000, v31
	v_cndmask_b32_e32 v31, v31, v44, vcc
	v_cmp_class_f32_e32 vcc, v30, v126
	s_nop 1
	v_cndmask_b32_e32 v30, v31, v30, vcc
	v_div_scale_f32 v31, s[18:19], v30, v30, 1.0
	v_rcp_f32_e32 v44, v31
	v_div_scale_f32 v45, vcc, 1.0, v30, 1.0
	s_mov_b32 s19, s44
	v_fma_f32 v46, -v31, v44, 1.0
	v_fmac_f32_e32 v44, v46, v44
	v_mul_f32_e32 v46, v45, v44
	v_fma_f32 v47, -v31, v46, v45
	v_fmac_f32_e32 v46, v47, v44
	v_fma_f32 v31, -v31, v46, v45
	v_div_fmas_f32 v31, v31, v44, v46
	v_div_fixup_f32 v30, v31, v30, 1.0
	v_pk_mul_f32 v[34:35], v[34:35], v[30:31] op_sel_hi:[1,0]
	v_pk_mul_f32 v[32:33], v[32:33], v[30:31] op_sel_hi:[1,0]
	v_pk_mul_f32 v[6:7], v[6:7], v[30:31] op_sel_hi:[1,0]
	v_pk_mul_f32 v[4:5], v[4:5], v[30:31] op_sel_hi:[1,0]
	v_pk_mul_f32 v[2:3], v[2:3], v[30:31] op_sel_hi:[1,0]
	v_pk_mul_f32 v[0:1], v[0:1], v[30:31] op_sel_hi:[1,0]
	s_andn2_b64 vcc, exec, s[46:47]
	s_waitcnt vmcnt(0)
	v_pk_mul_f32 v[8:9], v[160:161], v[34:35]
	v_lshlrev_b32_e32 v34, 16, v176
	v_and_b32_e32 v35, 0xffff0000, v176
	v_pk_mul_f32 v[10:11], v[162:163], v[32:33]
	v_lshlrev_b32_e32 v32, 16, v177
	v_and_b32_e32 v33, 0xffff0000, v177
	v_pk_mul_f32 v[8:9], v[8:9], v[34:35]
	v_pk_mul_f32 v[10:11], v[10:11], v[32:33]
	v_cvt_pk_bf16_f32 v8, v8, v9
	v_cvt_pk_bf16_f32 v9, v10, v11
	global_store_dwordx2 v[28:29], v[8:9], off
	v_pk_mul_f32 v[8:9], v[18:19], v[30:31] op_sel_hi:[1,0]
	v_lshlrev_b32_e32 v10, 16, v178
	v_pk_mul_f32 v[8:9], v[164:165], v[8:9]
	v_and_b32_e32 v11, 0xffff0000, v178
	v_pk_mul_f32 v[8:9], v[8:9], v[10:11]
	v_pk_mul_f32 v[10:11], v[16:17], v[30:31] op_sel_hi:[1,0]
	v_lshlrev_b32_e32 v12, 16, v179
	v_pk_mul_f32 v[10:11], v[166:167], v[10:11]
	v_and_b32_e32 v13, 0xffff0000, v179
	v_pk_mul_f32 v[10:11], v[10:11], v[12:13]
	v_cvt_pk_bf16_f32 v8, v8, v9
	v_cvt_pk_bf16_f32 v9, v10, v11
	global_store_dwordx2 v[28:29], v[8:9], off offset:16
	v_pk_mul_f32 v[6:7], v[6:7], v[168:169]
	v_lshlrev_b32_e32 v8, 16, v180
	v_and_b32_e32 v9, 0xffff0000, v180
	v_pk_mul_f32 v[6:7], v[6:7], v[8:9]
	v_pk_mul_f32 v[4:5], v[4:5], v[170:171]
	v_lshlrev_b32_e32 v8, 16, v181
	v_and_b32_e32 v9, 0xffff0000, v181
	v_pk_mul_f32 v[4:5], v[4:5], v[8:9]
	v_cvt_pk_bf16_f32 v6, v6, v7
	v_cvt_pk_bf16_f32 v7, v4, v5
	v_pk_mul_f32 v[2:3], v[2:3], v[172:173]
	v_lshlrev_b32_e32 v4, 16, v182
	v_and_b32_e32 v5, 0xffff0000, v182
	v_pk_mul_f32 v[2:3], v[2:3], v[4:5]
	v_pk_mul_f32 v[0:1], v[0:1], v[174:175]
	v_lshlrev_b32_e32 v4, 16, v183
	v_and_b32_e32 v5, 0xffff0000, v183
	v_pk_mul_f32 v[0:1], v[0:1], v[4:5]
	v_cvt_pk_bf16_f32 v2, v2, v3
	v_cvt_pk_bf16_f32 v3, v0, v1
	global_store_dwordx2 v[28:29], v[6:7], off offset:32
	global_store_dwordx2 v[28:29], v[2:3], off offset:48
	s_cbranch_vccz .LBB0_1433

; #define ALDS __attribute__((address_space(3)))
; __device__ __forceinline__ void r3_phase(ldsp lds, const bf16* U, const bf16* PREV, bf16* O, const float* gnw, int G, int bx, int wave, int lane) {
;     ...
;     for (int item = bx; item < N_ITEMS; item += G, ++k) {
;         const unsigned st = lds0 + (k & 1) * STAGE;
;         if (item + G < N_ITEMS) stage_item<true>(lds, ((k + 1) & 1) * STAGE, item + G, U, PREV, wave, lane);
;         int b, n, h; decode(item, b, n, h);
;         const float lg2 = log2f(1.0f - exp2f(-5.0f - (float)h));
;         bf16x8 qf[4];
; #pragma unroll
;         for (int ks = 0; ks < 4; ++ks) qf[ks] = *(const ALDS bf16x8*)(size_t)(st + off_b(32u * it + r, 8u + 2u * ks + hh));
;         bf16x8 pa[2][2];
;         const int irow = 32 * it + r;
; #pragma unroll
;         for (int sub = 0; sub < 2; ++sub) {
;             f32x16 s;
; #pragma unroll
;             for (int i = 0; i < 16; ++i) s[i] = 0.f;
; #pragma unroll
;             for (int ks = 0; ks < 4; ++ks) { const bf16x8 kf = *(const ALDS bf16x8*)(size_t)(st + off_b(32u * sub + r, 2u * ks + hh)); s = __builtin_amdgcn_mfma_f32_32x32x16_bf16(kf, qf[ks], s, 0, 0, 0); }
; #pragma unroll
;             for (int i = 0; i < 16; ++i) { const int jrow = 32 * sub + (i & 3) + 8 * (i >> 2) + 4 * hh; s[i] *= __builtin_amdgcn_exp2f(lg2 * fabsf((float)(irow - jrow))); }
;             pa[sub][0] = pack8s(s, 0); pa[sub][1] = pack8s(s, 8);
;         }
;     ...
;         const size_t tok = (size_t)b * SEQ + 64 * n + irow;
;         const float* gb = gnw; asm volatile("" : "+s"(gb));
;         const float* gp = gb + h * 128 + 32 * et + 4 * hh;
;         const bf16* gatep = U + tok * INW + 1536 + h * 128 + 32 * et + 4 * hh;
;         bf16* op = O + tok * D + h * 128 + 32 * et + 4 * hh;
;         f32x4 wq4[4]; v2u gq4[4];
; #pragma unroll
;         for (int g4 = 0; g4 < 4; ++g4) { wq4[g4] = *(const f32x4*)(gp + 8 * g4); gq4[g4] = *(const v2u*)(gatep + 8 * g4); }
.LBB0_1431:
	s_mul_hi_i32 s26, s19, 0x2aaaaaab
	s_lshr_b32 s4, s26, 31
	s_add_i32 s26, s26, s4
	s_ashr_i32 s70, s26, 6
	s_lshl_b32 s32, s26, 6
	s_mul_i32 s76, s26, 0xfffffd00
	s_ashr_i32 s71, s70, 31
	s_add_i32 s72, s33, s76
	s_lshl_b64 s[70:71], s[70:71], 12
	s_and_b32 s32, s32, 0xfc0
	s_ashr_i32 s73, s72, 31
	s_or_b32 s70, s70, s32
	s_lshl_b64 s[78:79], s[72:73], 2
	v_or_b32_e32 v184, s70, v60
	s_add_u32 s78, s24, s78
	s_addc_u32 s79, s25, s79
	s_lshl_b32 s32, s12, 2
	s_add_u32 s78, s78, s32
	s_addc_u32 s79, s79, 0
	v_lshlrev_b32_e32 v186, 2, v62
	v_mov_b32_e32 v187, v51
	v_mov_b64_e32 v[188:189], s[20:21]
	v_lshl_add_u64 v[190:191], s[78:79], 0, v[186:187]
	v_mad_u64_u32 v[188:189], vcc, v184, s13, v[188:189]
	v_mad_i32_i24 v189, s71, v127, v189
	s_lshl_b64 s[78:79], s[72:73], 1
	v_lshl_add_u64 v[188:189], v[188:189], 0, s[78:79]
	s_lshl_b32 s80, s12, 1
	s_mov_b32 s81, s27
	v_lshl_add_u64 v[188:189], v[188:189], 0, s[80:81]
	v_lshlrev_b32_e32 v186, 1, v62
	v_lshl_add_u64 v[192:193], v[188:189], 0, v[186:187]
	global_load_dwordx4 v[160:163], v[190:191], off
	global_load_dwordx2 v[176:177], v[192:193], off offset:3072
	global_load_dwordx4 v[164:167], v[190:191], off offset:32
	global_load_dwordx2 v[178:179], v[192:193], off offset:3088
	global_load_dwordx4 v[168:171], v[190:191], off offset:64
	global_load_dwordx2 v[180:181], v[192:193], off offset:3104
	global_load_dwordx4 v[172:175], v[190:191], off offset:96
	global_load_dwordx2 v[182:183], v[192:193], off offset:3120
	s_mul_i32 s4, s26, -6
	s_add_i32 s4, s19, s4
	v_cvt_f32_i32_e32 v0, s4
	s_mul_i32 s19, s18, 0xc000
	s_mov_b32 s5, 0xc2fc0000
	s_add_i32 s4, s19, 0
	v_sub_f32_e32 v0, 0xc0a00000, v0
	v_cmp_gt_f32_e32 vcc, s5, v0
	v_add_u32_e32 v24, s4, v61
	v_add_u32_e32 v26, s4, v63
	v_cndmask_b32_e32 v1, 0, v130, vcc
	v_add_f32_e32 v4, v0, v1
	v_add_u32_e32 v0, v24, v76
	ds_read_b128 v[0:3], v0
	v_exp_f32_e32 v25, v4
	v_add_u32_e32 v4, v26, v72
	ds_read_b128 v[36:39], v4
	v_add_u32_e32 v4, v24, v77
	ds_read_b128 v[4:7], v4
	s_waitcnt lgkmcnt(1)
	v_mfma_f32_32x32x16_bf16 v[8:23], v[0:3], v[36:39], 0
	v_add_u32_e32 v1, v26, v73
	s_and_b64 s[50:51], vcc, exec
	ds_read_b128 v[40:43], v1
	s_cselect_b32 s4, 0xffffffc0, 0
	v_ldexp_f32 v0, v25, s4
	v_sub_f32_e32 v25, 1.0, v0
	v_add_u32_e32 v0, v24, v78
	ds_read_b128 v[0:3], v0
	s_waitcnt lgkmcnt(1)
	v_mfma_f32_32x32x16_bf16 v[8:23], v[4:7], v[40:43], v[8:23]
	v_add_u32_e32 v27, v26, v74
	ds_read_b128 v[44:47], v27
	v_add_u32_e32 v4, v26, v75
	ds_read_b128 v[32:35], v4
	v_add_u32_e32 v4, v24, v79
	ds_read_b128 v[4:7], v4
	s_mov_b32 s4, 0x800000
	s_waitcnt lgkmcnt(2)
	v_mfma_f32_32x32x16_bf16 v[8:23], v[0:3], v[44:47], v[8:23]
	v_cmp_gt_f32_e32 vcc, s4, v25
	s_and_b64 s[50:51], vcc, exec
	s_cselect_b32 s4, 32, 0
	v_ldexp_f32 v0, v25, s4
	v_log_f32_e32 v0, v0
	v_cndmask_b32_e32 v1, 0, v131, vcc
	v_add_u32_e32 v144, 0x2000, v24
	s_waitcnt lgkmcnt(0)
	v_mfma_f32_32x32x16_bf16 v[8:23], v[4:7], v[32:35], v[8:23]
	v_sub_f32_e32 v50, v0, v1
	v_mul_f32_e64 v0, |v80|, v50
	v_mul_f32_e64 v1, |v81|, v50
	v_exp_f32_e32 v0, v0
	v_exp_f32_e32 v1, v1
	v_mul_f32_e64 v2, |v82|, v50
	v_mul_f32_e64 v3, |v83|, v50
	v_exp_f32_e32 v2, v2
	s_nop 3
	v_pk_mul_f32 v[28:29], v[0:1], v[8:9]
	v_mul_f32_e64 v0, |v88|, v50
	v_exp_f32_e32 v3, v3
	v_exp_f32_e32 v136, v0
	v_mul_f32_e64 v0, |v89|, v50
	v_exp_f32_e32 v137, v0
	v_mul_f32_e64 v0, |v90|, v50
	v_exp_f32_e32 v138, v0
	v_mul_f32_e64 v0, |v91|, v50
	v_mul_f32_e64 v4, |v84|, v50
	v_mul_f32_e64 v5, |v85|, v50
	v_exp_f32_e32 v139, v0
	v_add_u32_e32 v0, v144, v76
	v_exp_f32_e32 v4, v4
	v_exp_f32_e32 v5, v5
	v_pk_mul_f32 v[30:31], v[2:3], v[10:11]
	ds_read_b128 v[0:3], v0
	v_mul_f32_e64 v6, |v86|, v50
	v_mul_f32_e64 v7, |v87|, v50
	v_pk_mul_f32 v[132:133], v[4:5], v[12:13]
	v_mul_f32_e64 v4, |v92|, v50
	v_exp_f32_e32 v6, v6
	v_exp_f32_e32 v7, v7
	v_exp_f32_e32 v140, v4
	v_mul_f32_e64 v4, |v93|, v50
	v_exp_f32_e32 v141, v4
	v_mul_f32_e64 v4, |v94|, v50
	v_exp_f32_e32 v142, v4
	v_add_u32_e32 v4, v144, v77
	ds_read_b128 v[24:27], v4
	v_pk_mul_f32 v[134:135], v[6:7], v[14:15]
	s_waitcnt lgkmcnt(1)
	v_mfma_f32_32x32x16_bf16 v[0:15], v[0:3], v[36:39], 0
	v_mul_f32_e64 v136, v136, v16
	v_mul_f32_e64 v137, v137, v17
	v_add_u32_e32 v16, v144, v78
	v_mul_f32_e64 v138, v138, v18
	v_mul_f32_e64 v139, v139, v19
	ds_read_b128 v[16:19], v16
	v_mul_f32_e64 v143, |v95|, v50
	v_exp_f32_e32 v143, v143
	v_pk_mul_f32 v[140:141], v[140:141], v[20:21]
	s_waitcnt lgkmcnt(1)
	v_mfma_f32_32x32x16_bf16 v[0:15], v[24:27], v[40:43], v[0:15]
	v_add_u32_e32 v24, v144, v79
	ds_read_b128 v[24:27], v24
	v_mul_f32_e64 v142, v142, v22
	v_mul_f32_e64 v143, v143, v23
	v_cvt_pk_bf16_f32 v22, v132, v133
	v_cvt_pk_bf16_f32 v132, v136, v137
	v_cvt_pk_bf16_f32 v133, v138, v139
	v_cvt_pk_bf16_f32 v20, v28, v29
	s_waitcnt lgkmcnt(1)
	v_mfma_f32_32x32x16_bf16 v[0:15], v[16:19], v[44:47], v[0:15]
	v_mul_f32_e64 v16, |v96|, v50
	v_mul_f32_e64 v17, |v97|, v50
	v_exp_f32_e32 v16, v16
	v_exp_f32_e32 v17, v17
	v_mul_f32_e64 v18, |v102|, v50
	v_mul_f32_e64 v19, |v103|, v50
	v_exp_f32_e32 v18, v18
	s_waitcnt lgkmcnt(0)
; #define ALDS __attribute__((address_space(3)))
; __device__ __forceinline__ void r3_phase(ldsp lds, const bf16* U, const bf16* PREV, bf16* O, const float* gnw, int G, int bx, int wave, int lane) {
;     ...
;         f32x16 oin, ox;
; #pragma unroll
;         for (int i = 0; i < 16; ++i) { oin[i] = 0.f; ox[i] = 0.f; }
; #pragma unroll
;         for (int sub = 0; sub < 2; ++sub)
; #pragma unroll
;             for (int s2 = 0; s2 < 2; ++s2) oin = __builtin_amdgcn_mfma_f32_32x32x16_bf16(tr_perm(st + 16384, et, sub, s2, lane), pa[sub][s2], oin, 0, 0, 0);
; #pragma unroll
;         for (int ks = 0; ks < 4; ++ks) ox = __builtin_amdgcn_mfma_f32_32x32x16_bf16(tr_nat(st + 32768, et, ks, lane), qf[ks], ox, 0, 0, 0);
;         const float dec = __builtin_amdgcn_exp2f(lg2 * (float)(irow + 1));
;         float ssq = 0.f;
; #pragma unroll
;         for (int i = 0; i < 16; ++i) { oin[i] = fmaf(dec, ox[i], oin[i]); ssq += oin[i] * oin[i]; }
;         ssq += shx(ssq, 32);
;         ALDS float* red = (ALDS float*)(lds + RED_OFF + (k & 1) * 1024);
;         if (hh == 0) red[(et * 2 + it) * 32 + r] = ssq;
	v_mfma_f32_32x32x16_bf16 v[0:15], v[24:27], v[32:35], v[0:15]
	v_mul_f32_e64 v24, |v104|, v50
	v_mul_f32_e64 v25, |v105|, v50
	v_exp_f32_e32 v19, v19
	v_exp_f32_e32 v24, v24
	v_exp_f32_e32 v25, v25
	v_cvt_pk_bf16_f32 v21, v30, v31
	v_cvt_pk_bf16_f32 v23, v134, v135
	s_nop 4
	v_pk_mul_f32 v[136:137], v[16:17], v[0:1]
	v_mul_f32_e64 v0, |v98|, v50
	v_mul_f32_e64 v1, |v99|, v50
	v_exp_f32_e32 v0, v0
	v_exp_f32_e32 v1, v1
	v_mul_f32_e64 v16, |v100|, v50
	v_mul_f32_e64 v17, |v101|, v50
	v_exp_f32_e32 v16, v16
	v_pk_mul_f32 v[138:139], v[0:1], v[2:3]
	v_add_u32_e32 v2, s19, v67
	v_mul_f32_e64 v0, |v106|, v50
	v_add_u32_e32 v150, v2, v66
	v_exp_f32_e32 v144, v0
	v_add_u32_e32 v0, v150, v112
	v_add_u32_e32 v151, v113, v2
	ds_read_b64_tr_b16 v[0:1], v0
	ds_read_b64_tr_b16 v[2:3], v151 offset:2048
	v_exp_f32_e32 v17, v17
	v_cvt_pk_bf16_f32 v134, v140, v141
	v_cvt_pk_bf16_f32 v135, v142, v143
	v_pk_mul_f32 v[142:143], v[18:19], v[6:7]
	v_pk_mul_f32 v[140:141], v[16:17], v[4:5]
	v_mul_f32_e64 v4, |v107|, v50
	v_pk_mul_f32 v[8:9], v[24:25], v[8:9]
	v_exp_f32_e32 v145, v4
	v_mul_f32_e64 v4, |v108|, v50
	s_waitcnt lgkmcnt(0)
	v_mfma_f32_32x32x16_bf16 v[16:31], v[0:3], v[20:23], 0
	v_exp_f32_e32 v146, v4
	v_mul_f32_e64 v4, |v109|, v50
	v_exp_f32_e32 v147, v4
	v_add_u32_e32 v4, v114, v150
	ds_read_b64_tr_b16 v[4:5], v4
	ds_read_b64_tr_b16 v[6:7], v151 offset:6144
	v_mul_f32_e64 v0, |v110|, v50
	v_exp_f32_e32 v148, v0
	s_waitcnt lgkmcnt(0)
	v_mfma_f32_32x32x16_bf16 v[16:31], v[4:7], v[132:135], v[16:31]
	v_mul_f32_e64 v0, |v111|, v50
	v_exp_f32_e32 v149, v0
	v_add_u32_e32 v0, v115, v150
	ds_read_b64_tr_b16 v[0:1], v0
	ds_read_b64_tr_b16 v[2:3], v151 offset:10240
	v_cvt_pk_bf16_f32 v4, v136, v137
	v_cvt_pk_bf16_f32 v5, v138, v139
	v_cvt_pk_bf16_f32 v6, v140, v141
	v_cvt_pk_bf16_f32 v7, v142, v143
	v_add_u32_e32 v132, v116, v150
	ds_read_b64_tr_b16 v[132:133], v132
	ds_read_b64_tr_b16 v[134:135], v151 offset:14336
	s_waitcnt lgkmcnt(2)
	v_mfma_f32_32x32x16_bf16 v[16:31], v[0:3], v[4:7], v[16:31]
	v_mul_f32_e64 v2, v144, v10
	v_mul_f32_e64 v3, v145, v11
	v_mul_f32_e64 v4, v146, v12
	v_mul_f32_e64 v5, v147, v13
	v_mul_f32_e64 v6, v148, v14
	v_mul_f32_e64 v7, v149, v15
	v_cvt_pk_bf16_f32 v0, v8, v9
	v_cvt_pk_bf16_f32 v1, v2, v3
	v_cvt_pk_bf16_f32 v2, v4, v5
	v_cvt_pk_bf16_f32 v3, v6, v7
	s_lshl_b32 s4, s18, 10
	s_add_i32 s45, s4, 0
	s_waitcnt lgkmcnt(0)
	v_mfma_f32_32x32x16_bf16 v[16:31], v[132:135], v[0:3], v[16:31]
	v_add_u32_e32 v132, s19, v69
	v_add_u32_e32 v133, v132, v68
	v_add_u32_e32 v0, v133, v117
	v_add_u32_e32 v2, v132, v118
	ds_read_b64_tr_b16 v[0:1], v0
	ds_read_b64_tr_b16 v[2:3], v2
	s_add_i32 s45, s45, 0x18000
	s_waitcnt lgkmcnt(0)
	v_mfma_f32_32x32x16_bf16 v[0:15], v[0:3], v[36:39], 0
	v_add_u32_e32 v36, v119, v133
	v_add_u32_e32 v38, v132, v120
	ds_read_b64_tr_b16 v[36:37], v36
	ds_read_b64_tr_b16 v[38:39], v38
	s_waitcnt lgkmcnt(0)
	v_mfma_f32_32x32x16_bf16 v[0:15], v[36:39], v[40:43], v[0:15]
	v_add_u32_e32 v36, v121, v133
	v_add_u32_e32 v38, v132, v122
	ds_read_b64_tr_b16 v[36:37], v36
	ds_read_b64_tr_b16 v[38:39], v38
	v_mul_f32_e32 v40, v50, v70
	v_exp_f32_e32 v40, v40
	s_waitcnt lgkmcnt(0)
	v_mfma_f32_32x32x16_bf16 v[0:15], v[36:39], v[44:47], v[0:15]
	v_add_u32_e32 v36, v123, v133
	v_add_u32_e32 v38, v132, v124
	ds_read_b64_tr_b16 v[36:37], v36
	ds_read_b64_tr_b16 v[38:39], v38
	s_waitcnt lgkmcnt(0)
	v_mfma_f32_32x32x16_bf16 v[0:15], v[36:39], v[32:35], v[0:15]
	s_nop 11
	v_pk_fma_f32 v[34:35], v[40:41], v[0:1], v[16:17] op_sel_hi:[0,1,1]
	v_pk_mul_f32 v[36:37], v[34:35], v[34:35]
	v_pk_fma_f32 v[32:33], v[40:41], v[2:3], v[18:19] op_sel_hi:[0,1,1]
	v_pk_mul_f32 v[38:39], v[32:33], v[32:33]
	v_pk_fma_f32 v[16:17], v[40:41], v[6:7], v[22:23] op_sel_hi:[0,1,1]
	v_pk_fma_f32 v[6:7], v[40:41], v[8:9], v[24:25] op_sel_hi:[0,1,1]
	v_add_f32_e32 v24, v36, v37
	v_pk_fma_f32 v[18:19], v[40:41], v[4:5], v[20:21] op_sel_hi:[0,1,1]
	v_add_f32_e32 v24, v38, v24
	v_pk_mul_f32 v[20:21], v[18:19], v[18:19]
	v_add_f32_e32 v24, v39, v24
	v_add_f32_e32 v20, v20, v24
	v_pk_mul_f32 v[22:23], v[16:17], v[16:17]
	v_add_f32_e32 v20, v21, v20
	v_add_f32_e32 v20, v22, v20
	v_pk_mul_f32 v[8:9], v[6:7], v[6:7]
	v_add_f32_e32 v20, v23, v20
	v_pk_fma_f32 v[4:5], v[40:41], v[10:11], v[26:27] op_sel_hi:[0,1,1]
	v_add_f32_e32 v8, v8, v20
	v_pk_mul_f32 v[10:11], v[4:5], v[4:5]
	v_add_f32_e32 v8, v9, v8
	v_pk_fma_f32 v[2:3], v[40:41], v[12:13], v[28:29] op_sel_hi:[0,1,1]
	v_add_f32_e32 v8, v10, v8
	v_pk_mul_f32 v[12:13], v[2:3], v[2:3]
	v_add_f32_e32 v8, v11, v8
	v_pk_fma_f32 v[0:1], v[40:41], v[14:15], v[30:31] op_sel_hi:[0,1,1]
	v_add_f32_e32 v8, v12, v8
	v_mov_b32_e32 v9, v201
	v_pk_mul_f32 v[14:15], v[0:1], v[0:1]
	v_add_f32_e32 v8, v13, v8
	v_add_f32_e32 v8, v14, v8
	v_lshlrev_b32_e32 v9, 2, v9
	v_add_f32_e32 v8, v15, v8
	v_xor_b32_e32 v9, 0x80, v9
	ds_bpermute_b32 v9, v9, v8
	s_and_saveexec_b64 s[18:19], s[16:17]
	s_cbranch_execz .LBB0_1428
	s_add_i32 s4, s45, s7
	v_lshl_add_u32 v10, v49, 2, s4
	s_waitcnt lgkmcnt(0)
	v_add_f32_e32 v8, v8, v9
	ds_write_b32 v10, v8
	s_branch .LBB0_1428
